# opt49: opt47 + one static s_setprio 1 for waves 4-7 over both attention phases (reset to 0 at phase end)
# speedup vs baseline: 1.0070x; 1.0070x over previous
; __global__ void __launch_bounds__(512, 2) fwd_megakernel(Args a) {
;     ...
;         float lam;
;         { const float v1 = a.da_lambda[lane] * a.da_lambda[64 + lane], v2 = a.da_lambda[128 + lane] * a.da_lambda[192 + lane];
;           lam = __expf(wave_sum(v1)) - __expf(wave_sum(v2)) + 0.2f; }
;         for (int i = 0; i < 8; ++i) {
;             const int id = i * G + xvcu; if (id >= 2048) break;
;             int bh = id >> 4; const int qb = id & 15; int b = bh >> 3, h = bh & 7;
;             if (G == 256) { const int v4 = xvcu >> 4; h = (i + v4) & 7; b = 2 * i + (v4 >> 3); }
;             const float slope2 = exp2f(-(float)(h + 1)) * LOG2E;
.LBB0_843:
	s_or_b64 exec, exec, s[0:1]
	v_readfirstlane_b32 s93, v246
	s_bitcmp1_b32 s93, 8
	s_cbranch_scc0 .Lprio_skip
	s_setprio 1
.Lprio_skip:
	s_add_u32 s0, s48, 0x5600000
	s_addc_u32 s1, s49, 0
	v_writelane_b32 v254, s0, 59
	s_waitcnt lgkmcnt(0)
	v_lshlrev_b32_e32 v0, 2, v161
	v_writelane_b32 v254, s1, 60
	s_barrier
	v_readlane_b32 s0, v254, 9
	v_readlane_b32 s1, v254, 10
	s_nop 4
	global_load_dword v1, v0, s[0:1]
	global_load_dword v2, v0, s[0:1] offset:256
	global_load_dword v4, v0, s[0:1] offset:512
	s_nop 0
	global_load_dword v0, v0, s[0:1] offset:768
	v_mbcnt_hi_u32_b32 v6, -1, v172
	v_and_b32_e32 v7, 64, v6
	v_add_u32_e32 v7, 64, v7
	v_xor_b32_e32 v8, 1, v6
	v_cmp_lt_i32_e32 vcc, v8, v7
	s_cmpk_eq_i32 s50, 0x100
	s_cselect_b64 s[0:1], -1, 0
	v_cndmask_b32_e32 v8, v6, v8, vcc
	v_lshlrev_b32_e32 v8, 2, v8
	v_readlane_b32 s2, v254, 11
	v_readlane_b32 s3, v254, 12
	v_readlane_b32 s4, v254, 13
	v_readlane_b32 s5, v254, 14
	v_readlane_b32 s6, v254, 15
	v_readlane_b32 s7, v254, 16
	v_readlane_b32 s8, v254, 17
	v_readlane_b32 s9, v254, 18
	v_readlane_b32 s10, v254, 19
	v_readlane_b32 s11, v254, 20
	v_readlane_b32 s12, v254, 21
	v_readlane_b32 s13, v254, 22
	v_readlane_b32 s14, v254, 23
	v_readlane_b32 s15, v254, 24
	v_writelane_b32 v254, s0, 61
	s_mov_b32 s10, -2.0
	s_mov_b32 s12, -4.0
	v_writelane_b32 v254, s1, 62
	s_mov_b32 s14, 0xc0c00000
	v_readlane_b32 s1, v254, 38
	s_lshr_b32 s0, s1, 4
	v_writelane_b32 v254, s0, 63
	s_ashr_i32 s0, s1, 7
	v_writelane_b32 v255, s0, 0
	s_add_i32 s0, 0, 0x12000
	v_writelane_b32 v255, s0, 2
	s_add_i32 s0, 0, 0x16000
	v_writelane_b32 v255, s0, 3
	s_add_i32 s0, 0, 0x1a000
	v_writelane_b32 v255, s0, 4
	s_add_i32 s0, 0, 0x1e000
	v_writelane_b32 v255, s0, 5
	v_writelane_b32 v255, s48, 6
	s_mov_b32 s36, 0xc1800000
	s_mov_b32 s44, 0xc1900000
	v_writelane_b32 v255, s49, 7
	s_mov_b32 s46, 0xc1a00000
	s_mov_b32 s52, 0xc1b00000
	s_mov_b32 s54, 0xc2580000
	s_mov_b32 s56, 0xc2500000
	s_mov_b32 s58, 0xc2480000
	s_mov_b32 s60, 0xc2400000
	s_mov_b32 s62, 0xc2180000
	s_mov_b32 s64, 0xc2100000
	s_mov_b32 s66, 0xc2080000
	s_mov_b32 s74, 0xc2000000
	v_writelane_b32 v255, s50, 8
	s_mov_b32 s96, 0
	v_writelane_b32 v255, s96, 20
	v_mov_b32_e32 v165, 0
	s_mov_b32 s18, 0xc2fc0000
	s_mov_b32 s11, 0xc0400000
	s_mov_b32 s13, 0xc0a00000
	s_mov_b32 s15, 0xc0e00000
	s_mov_b32 s37, 0xc1880000
	s_mov_b32 s45, 0xc1980000
	s_mov_b32 s47, 0xc1a80000
	s_mov_b32 s53, 0xc1b80000
	s_mov_b32 s55, 0xc25c0000
	s_mov_b32 s57, 0xc2540000
	s_mov_b32 s59, 0xc24c0000
	s_mov_b32 s61, 0xc2440000
	s_mov_b32 s63, 0xc21c0000
	s_mov_b32 s65, 0xc2140000
	s_mov_b32 s67, 0xc20c0000
	s_mov_b32 s75, 0xc2040000
	v_mov_b32_e32 v178, 0x358637bd
	v_mov_b32_e32 v180, 0x42800000
	v_mov_b32_e32 v183, 0x42000000
	v_writelane_b32 v255, s51, 9
	s_waitcnt vmcnt(2)
	v_mul_f32_e32 v3, v1, v2
	ds_bpermute_b32 v3, v8, v3
	s_waitcnt vmcnt(0)
	v_mul_f32_e32 v5, v4, v0
	ds_bpermute_b32 v5, v8, v5
	s_waitcnt lgkmcnt(1)
	v_fmac_f32_e32 v3, v1, v2
	v_xor_b32_e32 v1, 2, v6
	v_cmp_lt_i32_e32 vcc, v1, v7
	s_waitcnt lgkmcnt(0)
	v_fmac_f32_e32 v5, v4, v0
	v_cndmask_b32_e32 v1, v6, v1, vcc
	v_lshlrev_b32_e32 v1, 2, v1
	ds_bpermute_b32 v2, v1, v3
	ds_bpermute_b32 v0, v1, v5
	s_waitcnt lgkmcnt(1)
	v_add_f32_e32 v2, v3, v2
	v_xor_b32_e32 v3, 4, v6
	v_cmp_lt_i32_e32 vcc, v3, v7
	s_waitcnt lgkmcnt(0)
	v_add_f32_e32 v0, v5, v0
	v_cndmask_b32_e32 v3, v6, v3, vcc
	v_lshlrev_b32_e32 v3, 2, v3
	ds_bpermute_b32 v9, v3, v2
	ds_bpermute_b32 v1, v3, v0
	s_waitcnt lgkmcnt(1)
	v_add_f32_e32 v2, v2, v9
	v_xor_b32_e32 v9, 8, v6
	v_cmp_lt_i32_e32 vcc, v9, v7
	s_waitcnt lgkmcnt(0)
	v_add_f32_e32 v0, v0, v1
	v_cndmask_b32_e32 v9, v6, v9, vcc
	v_lshlrev_b32_e32 v9, 2, v9
	ds_bpermute_b32 v10, v9, v2
	ds_bpermute_b32 v1, v9, v0
	s_waitcnt lgkmcnt(1)
	v_add_f32_e32 v2, v2, v10
	v_xor_b32_e32 v10, 16, v6
	v_cmp_lt_i32_e32 vcc, v10, v7
	s_waitcnt lgkmcnt(0)
	v_add_f32_e32 v0, v0, v1
	v_cndmask_b32_e32 v10, v6, v10, vcc
	v_lshlrev_b32_e32 v181, 2, v10
	ds_bpermute_b32 v10, v181, v2
	ds_bpermute_b32 v1, v181, v0
	s_waitcnt lgkmcnt(1)
	v_add_f32_e32 v2, v2, v10
	v_xor_b32_e32 v10, 32, v6
	v_cmp_lt_i32_e32 vcc, v10, v7
	s_waitcnt lgkmcnt(0)
	v_add_f32_e32 v0, v0, v1
	v_cndmask_b32_e32 v6, v6, v10, vcc
	v_lshlrev_b32_e32 v182, 2, v6
	ds_bpermute_b32 v6, v182, v2
	ds_bpermute_b32 v1, v182, v0
	s_waitcnt lgkmcnt(1)
	v_add_f32_e32 v2, v2, v6
	s_waitcnt lgkmcnt(0)
	v_add_f32_e32 v0, v0, v1
	v_mul_f32_e32 v2, 0x3fb8aa3b, v2
	v_mul_f32_e32 v0, 0x3fb8aa3b, v0
	v_exp_f32_e32 v2, v2
	v_exp_f32_e32 v0, v0
	s_nop 0
	v_sub_f32_e32 v0, v2, v0
	v_add_f32_e32 v162, 0x3e4ccccd, v0
	v_mov_b32_e32 v163, v162
	s_branch .LBB0_846

; __device__ __forceinline__ unsigned xb_add(unsigned* p, unsigned v) { return __hip_atomic_fetch_add(p, v, __ATOMIC_RELAXED, __HIP_MEMORY_SCOPE_AGENT); }
; __device__ __forceinline__ void xcd_barrier(const XcdBarrier& b) {
;     asm volatile("s_waitcnt vmcnt(0)" ::: "memory");
;     __syncthreads();
;     if (threadIdx.x == 0) {
;         unsigned* bar = b.bar;
;         __builtin_amdgcn_s_waitcnt(0);
;         unsigned nloc = b.st[0], nx = b.st[1];
;         if (nloc == 0u) { xcd_barrier_complete(bar, b.x, nloc, nx); b.st[0] = nloc; b.st[1] = nx; }
;         const unsigned old = xb_add(&bar[XB_XSUB(b.x)], 1u);
.LBB0_1014:
	s_setprio 0
	s_waitcnt vmcnt(0)
	s_barrier
	s_mov_b64 s[2:3], exec
	v_readlane_b32 s0, v254, 7
	v_readlane_b32 s1, v254, 8
	v_readlane_b32 s76, v254, 41
	v_readlane_b32 s66, v254, 49
	v_readlane_b32 s72, v254, 59
	s_and_b64 s[0:1], s[2:3], s[0:1]
	v_readlane_b32 s77, v254, 42
	v_readlane_b32 s78, v254, 43
	v_readlane_b32 s79, v254, 44
	v_readlane_b32 s80, v254, 45
	v_readlane_b32 s81, v254, 46
	v_readlane_b32 s82, v254, 47
	v_readlane_b32 s83, v254, 48
	v_readlane_b32 s64, v254, 27
	v_readlane_b32 s56, v254, 28
	v_readlane_b32 s67, v254, 50
	v_readlane_b32 s73, v254, 60
	s_mov_b64 exec, s[0:1]
	s_cbranch_execz .LBB0_1066
	s_add_i32 s0, 0, 0x20020
	v_mov_b32_e32 v0, s0
	s_waitcnt vmcnt(0) expcnt(0) lgkmcnt(0)
	ds_read_b32 v2, v0
	s_add_i32 s0, 0, 0x20024
	v_mov_b32_e32 v0, s0
	ds_read_b32 v0, v0
	s_waitcnt lgkmcnt(1)
	v_cmp_ne_u32_e32 vcc, 0, v2
	s_cbranch_vccnz .LBB0_1030
	s_add_u32 s8, s48, 0x100200
	s_addc_u32 s9, s49, 0
	s_add_u32 s10, s48, 0x100400
	s_addc_u32 s11, s49, 0
	s_add_u32 s12, s48, 0x100500
	s_addc_u32 s13, s49, 0
	s_add_u32 s14, s48, 0x100600
	s_addc_u32 s15, s49, 0
	s_add_u32 s36, s48, 0x100700
	s_addc_u32 s37, s49, 0
	s_add_u32 s38, s48, 0x100800
	s_addc_u32 s39, s49, 0
	s_add_u32 s40, s48, 0x100900
	s_addc_u32 s41, s49, 0
	s_add_u32 s42, s48, 0x100a00
	s_addc_u32 s43, s49, 0
	s_add_u32 s44, s48, 0x100b00
	s_addc_u32 s45, s49, 0
	s_add_u32 s46, s48, 0x100c00
	s_addc_u32 s47, s49, 0
	s_add_u32 s52, s48, 0x100d00
	s_addc_u32 s53, s49, 0
	s_add_u32 s54, s48, 0x100e00
	s_addc_u32 s55, s49, 0
	s_add_u32 s56, s48, 0x100f00
	s_addc_u32 s57, s49, 0
	s_add_u32 s58, s48, 0x101000
	s_addc_u32 s59, s49, 0
	s_add_u32 s60, s48, 0x101100
	s_addc_u32 s61, s49, 0
	s_add_u32 s62, s48, 0x101200
	v_readlane_b32 s0, v254, 1
	s_addc_u32 s63, s49, 0
	s_mul_i32 s0, s51, s0
	s_add_u32 s64, s48, 0x101300
	s_mul_i32 s0, s0, s50
	s_addc_u32 s65, s49, 0
	s_mov_b32 s1, 1
	v_mov_b32_e32 v16, 0
	s_branch .LBB0_1018
